# rw_prep per-channel parameters staged in LDS (18 fewer global loads per j pair)
# speedup vs baseline: 1.0047x; 1.0002x over previous
; DEVINL void rw_prep_unit(const Params& p, int unit) {
;     ...
;   }
;   __syncthreads();
;     ...
;         rw_shift4(colsb, *(const float4*)(p.rw_mu + c0), rowo, s, pr);
;         rw_shift4(colsb, *(const float4*)(p.rw_mu + 1024u + c0), rowo + 2048u, s, pkr);
;         rw_shift4(colsb, *(const float4*)(p.rw_mu + 2048u + c0), rowo + 4096u, s, pv);
;         const float4 a0q = *(const float4*)(p.rw_a0 + c0), kkq = *(const float4*)(p.rw_k_k + c0);
;         const float4 kaq = *(const float4*)(p.rw_k_a + c0), rkq = *(const float4*)(p.rw_r_k + c0);
;         const float4 w0fq = *(const float4*)(p.rw_w0_f + c0), w0bq = *(const float4*)(p.rw_w0_b + c0);
;         const float a0v[4] = {a0q.x, a0q.y, a0q.z, a0q.w}, kkp[4] = {kkq.x, kkq.y, kkq.z, kkq.w};
;         const float kap[4] = {kaq.x, kaq.y, kaq.z, kaq.w}, rkp[4] = {rkq.x, rkq.y, rkq.z, rkq.w};
;         const float w0f[4] = {w0fq.x, w0fq.y, w0fq.z, w0fq.w}, w0b[4] = {w0bq.x, w0bq.y, w0bq.z, w0bq.w};
.LBB0_380:
	s_or_b64 exec, exec, s[6:7]
	v_bfe_u32 v0, v2, 4, 2
	v_and_b32_e32 v180, 15, v2
	v_ashrrev_i32_e32 v1, 5, v2
	v_lshlrev_b32_e32 v182, 4, v0
	v_and_b32_e32 v181, -2, v1
	v_add_u32_e32 v183, 16, v182
	v_lshlrev_b32_e32 v184, 2, v180
	v_lshl_or_b32 v185, v0, 2, s52
	v_lshlrev_b32_e32 v186, 4, v180
	v_or_b32_e32 v187, 64, v182
	v_or_b32_e32 v188, 0x80, v182
	v_or_b32_e32 v190, 0xc0, v182
	s_mov_b32 s6, 0
	v_and_b32_e32 v200, 0xff, v2
	v_lshlrev_b32_e32 v200, 4, v200
	v_lshrrev_b32_e32 v201, 8, v2
	s_nop 0
	v_readfirstlane_b32 s55, v201
	s_nop 3
	s_cmp_eq_u32 s55, 0
	s_cbranch_scc0 .Lrwp_odd
	global_load_dwordx4 v[204:207], v200, s[90:91]
	global_load_dwordx4 v[208:211], v200, s[78:79]
	global_load_dwordx4 v[212:215], v200, s[26:27]
	global_load_dwordx4 v[216:219], v200, s[62:63]
	global_load_dwordx4 v[220:223], v200, s[16:17]
	s_waitcnt vmcnt(0)
	ds_write_b128 v200, v[204:207] offset:21504
	ds_write_b128 v200, v[208:211] offset:29696
	ds_write_b128 v200, v[212:215] offset:37888
	ds_write_b128 v200, v[216:219] offset:46080
	ds_write_b128 v200, v[220:223] offset:54272
	s_branch .Lrwp_join
.Lrwp_odd:
	global_load_dwordx4 v[204:207], v200, s[72:73]
	global_load_dwordx4 v[208:211], v200, s[20:21]
	global_load_dwordx4 v[212:215], v200, s[60:61]
	global_load_dwordx4 v[216:219], v200, s[12:13]
	s_waitcnt vmcnt(0)
	ds_write_b128 v200, v[204:207] offset:25600
	ds_write_b128 v200, v[208:211] offset:33792
	ds_write_b128 v200, v[212:215] offset:41984
	ds_write_b128 v200, v[216:219] offset:50176
.Lrwp_join:
	s_mov_b64 s[0:1], -1
	s_waitcnt lgkmcnt(0)
	s_barrier

; DEVINL void rw_shift4(const char* colsb, float4 mu, unsigned o, int s, float (&out)[4]) {
;   const unsigned op = (s > 0) ? o - (unsigned)(NCP * 2) : o;
;   const unsigned on = (s < S_ - 1) ? o + (unsigned)(NCP * 2) : o;
;   const uint2 c = *(const uint2*)(colsb + o);
;   uint2 pv = *(const uint2*)(colsb + op);
;   uint2 nx = *(const uint2*)(colsb + on);
;   if (s == 0) pv = make_uint2(0u, 0u);
;   if (s == S_ - 1) nx = make_uint2(0u, 0u);
;   const float cu[4] = {bflo(c.x), bfhi(c.x), bflo(c.y), bfhi(c.y)};
; DEVINL void rw_prep_unit(const Params& p, int unit) {
;     ...
;       for (int j = 0; j < 4; ++j) {
;         int jo = j, zo = 0;
;         asm volatile("" : "+v"(jo), "+v"(zo));
;         const int t = tok0 + mt * 16 + 4 * g + jo;
;         const int s = t & (S_ - 1), b = t >> 12;
;         const unsigned c0 = (unsigned)(head * 64 + l15 * 4 + zo);
;         const unsigned rowo = (unsigned)t * (unsigned)(NCP * 2) + (unsigned)(C_RW * 2) + c0 * 2u;
;         float pr[4], pkr[4], pv[4];
;         rw_shift4(colsb, *(const float4*)(p.rw_mu + c0), rowo, s, pr);
;         rw_shift4(colsb, *(const float4*)(p.rw_mu + 1024u + c0), rowo + 2048u, s, pkr);
;         rw_shift4(colsb, *(const float4*)(p.rw_mu + 2048u + c0), rowo + 4096u, s, pv);
;         const float4 a0q = *(const float4*)(p.rw_a0 + c0), kkq = *(const float4*)(p.rw_k_k + c0);
;         const float4 kaq = *(const float4*)(p.rw_k_a + c0), rkq = *(const float4*)(p.rw_r_k + c0);
;         const float4 w0fq = *(const float4*)(p.rw_w0_f + c0), w0bq = *(const float4*)(p.rw_w0_b + c0);
;         const float a0v[4] = {a0q.x, a0q.y, a0q.z, a0q.w}, kkp[4] = {kkq.x, kkq.y, kkq.z, kkq.w};
;         const float kap[4] = {kaq.x, kaq.y, kaq.z, kaq.w}, rkp[4] = {rkq.x, rkq.y, rkq.z, rkq.w};
;         const float w0f[4] = {w0fq.x, w0fq.y, w0fq.z, w0fq.w}, w0b[4] = {w0bq.x, w0bq.y, w0bq.z, w0bq.w};
;         float pk[4], av[4], kkv[4];
;         float n2 = 0.f, dot = 0.f;
; #pragma unroll
;         for (int n = 0; n < 4; ++n) {
;           const float kraw = pkr[n];
;           float a = sigm(a0v[n] + sel4(aa[n], j));
;           av[n] = a;
;           float kk = kraw * kkp[n];
;           kkv[n] = kk;
;           n2 += kk * kk;
;           float k2 = kraw * (1.f + (a - 1.f) * kap[n]);
;           pk[n] = k2;
;           dot += pr[n] * k2 * rkp[n];
;         }
.LBB0_383:
	s_nop 0
	v_mov_b32_e32 v64, s40
	v_mov_b32_e32 v65, 0
	s_cmp_eq_u32 s40, 2
	v_add_u32_e32 v96, v65, v192
	v_add_u32_e32 v194, v193, v64
	v_lshlrev_b32_e32 v178, 1, v96
	v_and_b32_e32 v212, 0xfff, v194
	v_mad_u64_u32 v[72:73], s[0:1], v194, s49, v[178:179]
	v_add_u32_e32 v68, 0x1840, v72
	v_lshlrev_b64 v[74:75], 2, v[96:97]
	v_cmp_eq_u32_e32 vcc, 0, v212
	v_add_u32_e32 v69, 0xffffc440, v72
	s_nop 0
	v_cndmask_b32_e32 v70, v69, v68, vcc
	v_cmp_eq_u32_e64 s[0:1], s44, v212
	v_add_u32_e32 v69, 0x6c40, v72
	ds_read_b128 v[64:67], v74 offset:21504
	v_cndmask_b32_e64 v73, v69, v68, s[0:1]
	global_load_dwordx2 v[68:69], v68, s[18:19]
	s_nop 0
	global_load_dwordx2 v[70:71], v70, s[18:19]
	s_nop 0
	global_load_dwordx2 v[76:77], v73, s[18:19]
	s_cselect_b64 s[6:7], -1, 0
	s_cmp_eq_u32 s40, 0
	s_cselect_b64 s[8:9], -1, 0
	v_cndmask_b32_e64 v223, v11, v10, s[6:7]
	v_cndmask_b32_e64 v223, v223, v8, s[8:9]
	s_waitcnt vmcnt(2) lgkmcnt(0)
	v_lshlrev_b32_e32 v209, 16, v68
	s_waitcnt vmcnt(1)
	v_cndmask_b32_e64 v70, v70, 0, vcc
	s_waitcnt vmcnt(0)
	v_cndmask_b32_e64 v73, v76, 0, s[0:1]
	v_cndmask_b32_e64 v76, v77, 0, s[0:1]
	v_and_b32_e32 v203, 0xffff0000, v68
	v_lshlrev_b32_e32 v68, 16, v70
	v_lshlrev_b32_e32 v77, 16, v73
	v_cndmask_b32_e64 v71, v71, 0, vcc
	v_lshlrev_b32_e32 v197, 16, v69
	v_and_b32_e32 v96, 0xffff0000, v69
	v_and_b32_e32 v69, 0xffff0000, v70
	v_and_b32_e32 v73, 0xffff0000, v73
	v_add_f32_e32 v68, v68, v77
	v_lshlrev_b32_e32 v70, 16, v71
	v_lshlrev_b32_e32 v78, 16, v76
	v_fma_f32 v210, v68, 0.5, -v209
	v_add_f32_e32 v68, v69, v73
	v_and_b32_e32 v71, 0xffff0000, v71
	v_and_b32_e32 v76, 0xffff0000, v76
	v_fma_f32 v204, v68, 0.5, -v203
	v_add_f32_e32 v68, v70, v78
	v_fma_f32 v198, v68, 0.5, -v197
	v_add_f32_e32 v68, v71, v76
	v_add_u32_e32 v73, 0x2040, v72
	v_add_u32_e32 v76, 0xffffcc40, v72
	v_cndmask_b32_e32 v78, v76, v73, vcc
	v_add_u32_e32 v76, 0x7440, v72
	v_fma_f32 v195, v68, 0.5, -v96
	s_nop 0
	v_cndmask_b32_e64 v80, v76, v73, s[0:1]
	ds_read_b128 v[68:71], v74 offset:25600
	s_nop 0
	global_load_dwordx2 v[76:77], v73, s[18:19]
	s_nop 0
	global_load_dwordx2 v[78:79], v78, s[18:19]
	s_nop 0
	global_load_dwordx2 v[80:81], v80, s[18:19]
	v_fma_f32 v222, v64, v210, v209
	v_fma_f32 v221, v65, v204, v203
	v_fma_f32 v220, v66, v198, v197
	v_fma_f32 v219, v67, v195, v96
	s_waitcnt vmcnt(2) lgkmcnt(0)
	v_lshlrev_b32_e32 v215, 16, v76
	s_waitcnt vmcnt(1)
	v_cndmask_b32_e64 v73, v78, 0, vcc
	v_cndmask_b32_e64 v78, v79, 0, vcc
	s_waitcnt vmcnt(0)
	v_cndmask_b32_e64 v79, v80, 0, s[0:1]
	v_cndmask_b32_e64 v80, v81, 0, s[0:1]
	v_and_b32_e32 v208, 0xffff0000, v76
	v_lshlrev_b32_e32 v76, 16, v73
	v_lshlrev_b32_e32 v81, 16, v79
	v_add_f32_e32 v76, v76, v81
	v_and_b32_e32 v73, 0xffff0000, v73
	v_and_b32_e32 v79, 0xffff0000, v79
	v_fma_f32 v76, v76, 0.5, -v215
	v_fmac_f32_e32 v215, v68, v76
	v_add_f32_e32 v68, v73, v79
	v_lshlrev_b32_e32 v201, 16, v77
	v_and_b32_e32 v196, 0xffff0000, v77
	v_lshlrev_b32_e32 v77, 16, v78
	v_lshlrev_b32_e32 v82, 16, v80
	v_fma_f32 v68, v68, 0.5, -v208
	v_fmac_f32_e32 v208, v69, v68
	v_add_f32_e32 v68, v77, v82
	v_and_b32_e32 v78, 0xffff0000, v78
	v_and_b32_e32 v80, 0xffff0000, v80
	v_fma_f32 v68, v68, 0.5, -v201
	v_fmac_f32_e32 v201, v70, v68
	v_add_f32_e32 v68, v78, v80
	v_fma_f32 v68, v68, 0.5, -v196
	v_add_u32_e32 v73, 0x2840, v72
	v_add_u32_e32 v76, 0xffffd440, v72
	v_add_u32_e32 v72, 0x7c40, v72
	v_fmac_f32_e32 v196, v71, v68
	s_nop 0
	v_cndmask_b32_e32 v76, v76, v73, vcc
	v_cndmask_b32_e64 v78, v72, v73, s[0:1]
	ds_read_b128 v[68:71], v74 offset:29696
	s_nop 0
	global_load_dwordx2 v[72:73], v73, s[18:19]
	s_nop 0
	global_load_dwordx2 v[76:77], v76, s[18:19]
	s_nop 0
	global_load_dwordx2 v[78:79], v78, s[18:19]
	s_waitcnt vmcnt(2) lgkmcnt(0)
	v_lshlrev_b32_e32 v216, 16, v72
	s_waitcnt vmcnt(1)
	v_cndmask_b32_e64 v76, v76, 0, vcc
	s_waitcnt vmcnt(0)
	v_cndmask_b32_e64 v78, v78, 0, s[0:1]
	v_and_b32_e32 v211, 0xffff0000, v72
	v_lshlrev_b32_e32 v72, 16, v76
	v_lshlrev_b32_e32 v80, 16, v78
	v_cndmask_b32_e64 v77, v77, 0, vcc
	v_cndmask_b32_e64 v79, v79, 0, s[0:1]
	v_lshlrev_b32_e32 v205, 16, v73
	v_and_b32_e32 v199, 0xffff0000, v73
	v_and_b32_e32 v73, 0xffff0000, v76
	v_and_b32_e32 v78, 0xffff0000, v78
	v_add_f32_e32 v72, v72, v80
	v_lshlrev_b32_e32 v76, 16, v77
	v_lshlrev_b32_e32 v81, 16, v79
	v_fma_f32 v218, v72, 0.5, -v216
	v_add_f32_e32 v72, v73, v78
	v_and_b32_e32 v77, 0xffff0000, v77
	v_and_b32_e32 v79, 0xffff0000, v79
	v_fma_f32 v214, v72, 0.5, -v211
	v_add_f32_e32 v72, v76, v81
	v_fma_f32 v207, v72, 0.5, -v205
	v_add_f32_e32 v72, v77, v79
	v_fma_f32 v202, v72, 0.5, -v199
	s_nop 0
	ds_read_b128 v[92:95], v74 offset:33792
	s_nop 0
	ds_read_b128 v[88:91], v74 offset:37888
	s_nop 0
	ds_read_b128 v[84:87], v74 offset:41984
	s_nop 0
	ds_read_b128 v[80:83], v74 offset:46080
	s_nop 0
	ds_read_b128 v[76:79], v74 offset:50176
	s_nop 0
	ds_read_b128 v[72:75], v74 offset:54272
	v_fma_f32 v217, v68, v218, v216
	v_fma_mixlo_f16 v68, v68, v218, v216
	v_fma_f32 v213, v69, v214, v211
	v_fma_mixlo_f16 v69, v69, v214, v211
	v_fma_f32 v206, v70, v207, v205
	v_fma_mixlo_f16 v70, v70, v207, v205
	v_fma_f32 v200, v71, v202, v199
	v_fma_mixlo_f16 v71, v71, v202, v199
	s_waitcnt lgkmcnt(5)
	v_add_f32_e32 v92, v92, v223
	v_mul_f32_e32 v92, 0xbfb8aa3b, v92
	v_exp_f32_e32 v92, v92
	s_waitcnt lgkmcnt(4)
	v_mul_f32_e32 v89, v208, v89
	v_mul_f32_e32 v88, v215, v88
	v_mul_f32_e32 v90, v201, v90
	v_add_f32_e32 v92, 1.0, v92
	v_div_scale_f32 v223, s[0:1], v92, v92, 1.0
	v_rcp_f32_e32 v224, v223
	v_mul_f32_e32 v91, v196, v91
	v_fma_f32 v225, -v223, v224, 1.0
	v_fmac_f32_e32 v224, v225, v224
	v_div_scale_f32 v225, vcc, 1.0, v92, 1.0
	v_mul_f32_e32 v226, v225, v224
	v_fma_f32 v227, -v223, v226, v225
	v_fmac_f32_e32 v226, v227, v224
	v_fma_f32 v223, -v223, v226, v225
	v_div_fmas_f32 v223, v223, v224, v226
	v_div_fixup_f32 v92, v223, v92, 1.0
	v_add_f32_e32 v223, -1.0, v92
	s_waitcnt lgkmcnt(3)
; DEVINL u16 f2bf(float a) { return (u16)(pk2(a, 0.f) & 0xffffu); }
; DEVINL float sigm(float x) { return 1.f / (1.f + __expf(-x)); }
; DEVINL void rw_prep_unit(const Params& p, int unit) {
;     ...
; #pragma unroll
;         for (int n = 0; n < 4; ++n) {
;           const float kraw = pkr[n];
;           float a = sigm(a0v[n] + sel4(aa[n], j));
;           av[n] = a;
;           float kk = kraw * kkp[n];
;           kkv[n] = kk;
;           n2 += kk * kk;
;           float k2 = kraw * (1.f + (a - 1.f) * kap[n]);
;           pk[n] = k2;
;           dot += pr[n] * k2 * rkp[n];
;         }
;         n2 = allred16(n2);
;         dot = allred16(dot);
;         const float inv = 1.f / fmaxf(sqrtf(n2), 1e-12f);
;         const unsigned reco = ((unsigned)((b * 16 + head) * 4096 + s)) * 1024u;
;         const unsigned tco = (unsigned)t * 2048u + c0 * 2u;
;         unsigned hwf[4], hwb[4], ha[4], hb[4], hk[4], hr[4], hv[4], bg[4], bbn[4];
; #pragma unroll
;         for (int n = 0; n < 4; ++n) {
;           float wf = __expf(-0.606531f * sigm(w0f[n] + sel4(awf[n], j)));
;           float wb = __expf(-0.606531f * sigm(w0b[n] + sel4(awb[n], j)));
;           float kkn = kkv[n] * inv;
;           hwf[n] = f2h(wf); hwb[n] = f2h(wb); ha[n] = f2h(-kkn); hb[n] = f2h(kkn * av[n]);
;           hk[n] = f2h(pk[n]); hr[n] = f2h(pr[n]); hv[n] = f2h(pv[n]);
;           bg[n] = f2bf(sel4(ag[n], j)); bbn[n] = f2bf(dot * pv[n]);
;         }
	v_fma_f32 v84, v84, v223, 1.0
	v_mul_f32_e32 v223, v215, v84
	v_mul_f32_e32 v222, v222, v223
	s_waitcnt lgkmcnt(2)
	v_fma_f32 v80, v80, v222, 0
	v_cndmask_b32_e64 v222, v23, v22, s[6:7]
	v_cndmask_b32_e64 v222, v222, v20, s[8:9]
	v_add_f32_e32 v93, v93, v222
	v_mul_f32_e32 v93, 0xbfb8aa3b, v93
	v_exp_f32_e32 v93, v93
	v_fma_mixlo_f16 v84, v215, v84, 0
	v_add_f32_e32 v93, 1.0, v93
	v_div_scale_f32 v222, s[0:1], v93, v93, 1.0
	v_rcp_f32_e32 v223, v222
	s_nop 0
	v_fma_f32 v224, -v222, v223, 1.0
	v_fmac_f32_e32 v223, v224, v223
	v_div_scale_f32 v224, vcc, 1.0, v93, 1.0
	v_mul_f32_e32 v225, v224, v223
	v_fma_f32 v226, -v222, v225, v224
	v_fmac_f32_e32 v225, v226, v223
	v_fma_f32 v222, -v222, v225, v224
	v_div_fmas_f32 v222, v222, v223, v225
	v_div_fixup_f32 v93, v222, v93, 1.0
	v_add_f32_e32 v223, -1.0, v93
	v_fma_f32 v85, v85, v223, 1.0
	v_mul_f32_e32 v223, v208, v85
	v_mul_f32_e32 v221, v221, v223
	v_fmac_f32_e32 v80, v81, v221
	v_cndmask_b32_e64 v81, v35, v34, s[6:7]
	v_cndmask_b32_e64 v81, v81, v32, s[8:9]
	v_add_f32_e32 v81, v94, v81
	v_mul_f32_e32 v81, 0xbfb8aa3b, v81
	v_exp_f32_e32 v81, v81
	v_mul_f32_e32 v222, v89, v89
	v_fmac_f32_e32 v222, v88, v88
	v_fmac_f32_e32 v222, v90, v90
	v_add_f32_e32 v81, 1.0, v81
	v_div_scale_f32 v94, s[0:1], v81, v81, 1.0
	v_rcp_f32_e32 v221, v94
	v_fmac_f32_e32 v222, v91, v91
	v_fma_mixlo_f16 v85, v208, v85, 0
	v_fma_f32 v223, -v94, v221, 1.0
	v_fmac_f32_e32 v221, v223, v221
	v_div_scale_f32 v223, vcc, 1.0, v81, 1.0
	v_mul_f32_e32 v224, v223, v221
	v_fma_f32 v225, -v94, v224, v223
	v_fmac_f32_e32 v224, v225, v221
	v_fma_f32 v94, -v94, v224, v223
	v_div_fmas_f32 v94, v94, v221, v224
	v_div_fixup_f32 v81, v94, v81, 1.0
	v_add_f32_e32 v94, -1.0, v81
	v_fma_f32 v86, v86, v94, 1.0
	v_mul_f32_e32 v94, v201, v86
	v_mul_f32_e32 v94, v220, v94
	v_fmac_f32_e32 v80, v82, v94
	v_cndmask_b32_e64 v82, v47, v46, s[6:7]
	v_cndmask_b32_e64 v82, v82, v44, s[8:9]
	v_add_f32_e32 v82, v95, v82
	v_mul_f32_e32 v82, 0xbfb8aa3b, v82
	v_exp_f32_e32 v82, v82
	s_nop 0
	v_add_f32_e32 v82, 1.0, v82
	v_div_scale_f32 v94, s[0:1], v82, v82, 1.0
	v_rcp_f32_e32 v95, v94
	s_nop 0
	v_fma_f32 v220, -v94, v95, 1.0
	v_fmac_f32_e32 v95, v220, v95
	v_div_scale_f32 v220, vcc, 1.0, v82, 1.0
	v_mul_f32_e32 v221, v220, v95
	v_fma_f32 v223, -v94, v221, v220
	v_fmac_f32_e32 v221, v223, v95
	v_fma_f32 v94, -v94, v221, v220
	v_div_fmas_f32 v94, v94, v95, v221
	v_div_fixup_f32 v82, v94, v82, 1.0
	v_add_f32_e32 v94, -1.0, v82
	v_fma_f32 v87, v87, v94, 1.0
	v_mul_f32_e32 v94, v196, v87
	v_mul_f32_e32 v94, v219, v94
	v_fmac_f32_e32 v80, v83, v94
	v_add_f32_dpp v83, v222, v222 quad_perm:[1,0,3,2] row_mask:0xf bank_mask:0xf bound_ctrl:1
	s_nop 0
	v_add_f32_dpp v80, v80, v80 quad_perm:[1,0,3,2] row_mask:0xf bank_mask:0xf bound_ctrl:1
	v_add_f32_dpp v83, v83, v83 quad_perm:[2,3,0,1] row_mask:0xf bank_mask:0xf bound_ctrl:1
	s_nop 0
	v_add_f32_dpp v80, v80, v80 quad_perm:[2,3,0,1] row_mask:0xf bank_mask:0xf bound_ctrl:1
	v_add_f32_dpp v83, v83, v83 row_half_mirror row_mask:0xf bank_mask:0xf bound_ctrl:1
	s_nop 0
	v_add_f32_dpp v80, v80, v80 row_half_mirror row_mask:0xf bank_mask:0xf bound_ctrl:1
	v_add_f32_dpp v83, v83, v83 row_mirror row_mask:0xf bank_mask:0xf bound_ctrl:1
	v_cmp_gt_f32_e32 vcc, s50, v83
	v_mul_f32_e32 v94, 0x4f800000, v83
	v_add_f32_dpp v80, v80, v80 row_mirror row_mask:0xf bank_mask:0xf bound_ctrl:1
	v_cndmask_b32_e32 v83, v83, v94, vcc
	v_sqrt_f32_e32 v94, v83
	s_nop 0
	v_add_u32_e32 v95, -1, v94
	v_fma_f32 v219, -v95, v94, v83
	v_cmp_ge_f32_e64 s[0:1], 0, v219
	v_add_u32_e32 v219, 1, v94
	s_nop 0
	v_cndmask_b32_e64 v95, v94, v95, s[0:1]
	v_fma_f32 v94, -v219, v94, v83
	v_cmp_lt_f32_e64 s[0:1], 0, v94
	s_nop 1
	v_cndmask_b32_e64 v94, v95, v219, s[0:1]
	v_mul_f32_e32 v95, 0x37800000, v94
	v_cndmask_b32_e32 v94, v94, v95, vcc
	v_cmp_class_f32_e32 vcc, v83, v179
	s_nop 1
	v_cndmask_b32_e32 v83, v94, v83, vcc
	v_max_f32_e32 v83, 0x2b8cbccc, v83
	v_div_scale_f32 v94, s[0:1], v83, v83, 1.0
	v_rcp_f32_e32 v95, v94
	s_nop 0
	v_fma_f32 v219, -v94, v95, 1.0
	v_fmac_f32_e32 v95, v219, v95
	v_div_scale_f32 v219, vcc, 1.0, v83, 1.0
	v_mul_f32_e32 v220, v219, v95
	v_fma_f32 v221, -v94, v220, v219
	v_fmac_f32_e32 v220, v221, v95
	v_fma_f32 v94, -v94, v220, v219
	v_div_fmas_f32 v94, v94, v95, v220
	v_lshlrev_b32_e32 v95, 10, v212
	v_cndmask_b32_e64 v212, v3, v2, s[6:7]
	v_cndmask_b32_e64 v212, v212, v0, s[8:9]
	s_waitcnt lgkmcnt(1)
	v_add_f32_e32 v76, v76, v212
	v_mul_f32_e32 v76, 0xbfb8aa3b, v76
	v_exp_f32_e32 v76, v76
	v_div_fixup_f32 v83, v94, v83, 1.0
	v_mul_f32_e32 v88, v88, v83
	v_lshrrev_b32_e32 v94, 8, v194
	v_add_f32_e32 v76, 1.0, v76
	v_div_scale_f32 v212, s[0:1], v76, v76, 1.0
	v_rcp_f32_e32 v219, v212
	v_and_b32_e32 v94, 0x3f0, v94
	v_fma_f32 v220, -v212, v219, 1.0
	v_fmac_f32_e32 v219, v220, v219
	v_div_scale_f32 v220, vcc, 1.0, v76, 1.0
	v_mul_f32_e32 v221, v220, v219
	v_fma_f32 v222, -v212, v221, v220
	v_fmac_f32_e32 v221, v222, v219
	v_fma_f32 v212, -v212, v221, v220
	v_div_fmas_f32 v212, v212, v219, v221
	v_div_fixup_f32 v76, v212, v76, 1.0
	v_cndmask_b32_e64 v212, v7, v6, s[6:7]
	v_cndmask_b32_e64 v212, v212, v4, s[8:9]
	s_waitcnt lgkmcnt(0)
; DEVINL u16 f2bf(float a) { return (u16)(pk2(a, 0.f) & 0xffffu); }
; DEVINL float sigm(float x) { return 1.f / (1.f + __expf(-x)); }
; DEVINL void rw_prep_unit(const Params& p, int unit) {
;     ...
; #pragma unroll
;         for (int n = 0; n < 4; ++n) {
;           float wf = __expf(-0.606531f * sigm(w0f[n] + sel4(awf[n], j)));
;           float wb = __expf(-0.606531f * sigm(w0b[n] + sel4(awb[n], j)));
;           float kkn = kkv[n] * inv;
;           hwf[n] = f2h(wf); hwb[n] = f2h(wb); ha[n] = f2h(-kkn); hb[n] = f2h(kkn * av[n]);
;           hk[n] = f2h(pk[n]); hr[n] = f2h(pr[n]); hv[n] = f2h(pv[n]);
;           bg[n] = f2bf(sel4(ag[n], j)); bbn[n] = f2bf(dot * pv[n]);
;         }
	v_add_f32_e32 v72, v72, v212
	v_mul_f32_e32 v72, 0xbfb8aa3b, v72
	v_exp_f32_e32 v72, v72
	v_mul_f32_e32 v76, 0xbf1b459e, v76
	v_mul_f32_e32 v76, 0x3fb8aa3b, v76
	v_exp_f32_e32 v76, v76
	v_add_f32_e32 v72, 1.0, v72
	v_div_scale_f32 v212, s[0:1], v72, v72, 1.0
	v_rcp_f32_e32 v219, v212
	v_cvt_f16_f32_e32 v76, v76
	v_fma_f32 v220, -v212, v219, 1.0
	v_fmac_f32_e32 v219, v220, v219
	v_div_scale_f32 v220, vcc, 1.0, v72, 1.0
	v_mul_f32_e32 v221, v220, v219
	v_fma_f32 v222, -v212, v221, v220
	v_fmac_f32_e32 v221, v222, v219
	v_fma_f32 v212, -v212, v221, v220
	v_div_fmas_f32 v212, v212, v219, v221
	v_div_fixup_f32 v72, v212, v72, 1.0
	v_cvt_f16_f32_e64 v212, -v88
	v_fma_mixlo_f16 v88, v92, v88, 0
	v_fma_mixlo_f16 v92, v64, v210, v209
	v_cndmask_b32_e64 v64, v51, v50, s[6:7]
	v_cndmask_b32_e64 v64, v64, v48, s[8:9]
	v_cvt_pk_bf16_f32 v209, v64, s0
	v_mul_f32_e32 v64, v217, v80
	v_cvt_pk_bf16_f32 v210, v64, s0
	v_cndmask_b32_e64 v64, v15, v14, s[6:7]
	v_cndmask_b32_e64 v64, v64, v12, s[8:9]
	v_add_f32_e32 v64, v77, v64
	v_mul_f32_e32 v64, 0xbfb8aa3b, v64
	v_exp_f32_e32 v64, v64
	v_mul_f32_e32 v72, 0xbf1b459e, v72
	v_mul_f32_e32 v72, 0x3fb8aa3b, v72
	v_exp_f32_e32 v72, v72
	v_add_f32_e32 v64, 1.0, v64
	v_div_scale_f32 v77, s[0:1], v64, v64, 1.0
	v_rcp_f32_e32 v215, v77
	v_cvt_f16_f32_e32 v72, v72
	v_fma_f32 v216, -v77, v215, 1.0
	v_fmac_f32_e32 v215, v216, v215
	v_div_scale_f32 v216, vcc, 1.0, v64, 1.0
	v_mul_f32_e32 v217, v216, v215
	v_fma_f32 v218, -v77, v217, v216
	v_fmac_f32_e32 v217, v218, v215
	v_fma_f32 v77, -v77, v217, v216
	v_div_fmas_f32 v77, v77, v215, v217
	v_div_fixup_f32 v64, v77, v64, 1.0
	v_cndmask_b32_e64 v77, v19, v18, s[6:7]
	v_cndmask_b32_e64 v77, v77, v16, s[8:9]
	v_add_f32_e32 v73, v73, v77
	v_mul_f32_e32 v73, 0xbfb8aa3b, v73
	v_exp_f32_e32 v73, v73
	v_mul_f32_e32 v64, 0xbf1b459e, v64
	v_mul_f32_e32 v64, 0x3fb8aa3b, v64
	v_exp_f32_e32 v64, v64
	v_add_f32_e32 v73, 1.0, v73
	v_div_scale_f32 v77, s[0:1], v73, v73, 1.0
	v_rcp_f32_e32 v215, v77
	v_cvt_f16_f32_sdwa v64, v64 dst_sel:WORD_1 dst_unused:UNUSED_PAD src0_sel:DWORD
	v_fma_f32 v216, -v77, v215, 1.0
	v_fmac_f32_e32 v215, v216, v215
	v_div_scale_f32 v216, vcc, 1.0, v73, 1.0
	v_mul_f32_e32 v217, v216, v215
	v_fma_f32 v218, -v77, v217, v216
	v_fmac_f32_e32 v217, v218, v215
	v_fma_f32 v77, -v77, v217, v216
	v_div_fmas_f32 v77, v77, v215, v217
	v_div_fixup_f32 v73, v77, v73, 1.0
	v_mul_f32_e32 v77, v89, v83
	v_cvt_f16_f32_sdwa v89, -v77 dst_sel:WORD_1 dst_unused:UNUSED_PAD src0_sel:DWORD
	v_fma_mixlo_f16 v77, v93, v77, 0
	v_fma_mixlo_f16 v93, v65, v204, v203
	v_cndmask_b32_e64 v65, v55, v54, s[6:7]
	v_cndmask_b32_e64 v65, v65, v52, s[8:9]
	v_cvt_pk_bf16_f32 v203, v65, s0
	v_mul_f32_e32 v65, v213, v80
	v_cvt_pk_bf16_f32 v204, v65, s0
	v_cndmask_b32_e64 v65, v27, v26, s[6:7]
	v_cndmask_b32_e64 v65, v65, v24, s[8:9]
	v_add_f32_e32 v65, v78, v65
	v_mul_f32_e32 v65, 0xbfb8aa3b, v65
	v_exp_f32_e32 v65, v65
	v_mul_f32_e32 v73, 0xbf1b459e, v73
	v_mul_f32_e32 v73, 0x3fb8aa3b, v73
	v_exp_f32_e32 v73, v73
	v_add_f32_e32 v65, 1.0, v65
	v_div_scale_f32 v78, s[0:1], v65, v65, 1.0
	v_rcp_f32_e32 v208, v78
	v_cvt_f16_f32_sdwa v73, v73 dst_sel:WORD_1 dst_unused:UNUSED_PAD src0_sel:DWORD
	v_or_b32_e32 v64, v64, v76
	v_fma_f32 v211, -v78, v208, 1.0
	v_fmac_f32_e32 v208, v211, v208
	v_div_scale_f32 v211, vcc, 1.0, v65, 1.0
	v_mul_f32_e32 v213, v211, v208
	v_fma_f32 v214, -v78, v213, v211
	v_fmac_f32_e32 v213, v214, v208
	v_fma_f32 v78, -v78, v213, v211
	v_div_fmas_f32 v78, v78, v208, v213
	v_div_fixup_f32 v65, v78, v65, 1.0
	v_cndmask_b32_e64 v78, v31, v30, s[6:7]
	v_cndmask_b32_e64 v78, v78, v28, s[8:9]
	v_add_f32_e32 v74, v74, v78
	v_mul_f32_e32 v74, 0xbfb8aa3b, v74
	v_exp_f32_e32 v74, v74
	v_mul_f32_e32 v65, 0xbf1b459e, v65
	v_mul_f32_e32 v65, 0x3fb8aa3b, v65
	v_exp_f32_e32 v65, v65
	v_add_f32_e32 v74, 1.0, v74
	v_div_scale_f32 v78, s[0:1], v74, v74, 1.0
	v_rcp_f32_e32 v208, v78
	v_cvt_f16_f32_e32 v65, v65
	v_fma_f32 v211, -v78, v208, 1.0
	v_fmac_f32_e32 v208, v211, v208
	v_div_scale_f32 v211, vcc, 1.0, v74, 1.0
	v_mul_f32_e32 v213, v211, v208
	v_fma_f32 v214, -v78, v213, v211
	v_fmac_f32_e32 v213, v214, v208
	v_fma_f32 v78, -v78, v213, v211
	v_div_fmas_f32 v78, v78, v208, v213
	v_div_fixup_f32 v74, v78, v74, 1.0
	v_mul_f32_e32 v78, v90, v83
	v_cvt_f16_f32_e64 v90, -v78
	v_fma_mixlo_f16 v78, v81, v78, 0
	v_fma_mixlo_f16 v81, v201, v86, 0
	v_fma_mixlo_f16 v86, v66, v198, v197
	v_cndmask_b32_e64 v66, v59, v58, s[6:7]
	v_cndmask_b32_e64 v66, v66, v56, s[8:9]
	v_cvt_pk_bf16_f32 v197, v66, s0
	v_mul_f32_e32 v66, v206, v80
	v_cvt_pk_bf16_f32 v198, v66, s0
	v_cndmask_b32_e64 v66, v39, v38, s[6:7]
	v_cndmask_b32_e64 v66, v66, v36, s[8:9]
	v_add_f32_e32 v66, v79, v66
	v_mul_f32_e32 v66, 0xbfb8aa3b, v66
	v_exp_f32_e32 v66, v66
	v_mul_f32_e32 v74, 0xbf1b459e, v74
	v_mul_f32_e32 v74, 0x3fb8aa3b, v74
	v_exp_f32_e32 v74, v74
	v_add_f32_e32 v66, 1.0, v66
	v_div_scale_f32 v79, s[0:1], v66, v66, 1.0
	v_rcp_f32_e32 v201, v79
	v_cvt_f16_f32_e32 v74, v74
	v_fma_f32 v205, -v79, v201, 1.0
	v_fmac_f32_e32 v201, v205, v201
	v_div_scale_f32 v205, vcc, 1.0, v66, 1.0
	v_mul_f32_e32 v206, v205, v201
	v_fma_f32 v207, -v79, v206, v205
	v_fmac_f32_e32 v206, v207, v201
	v_fma_f32 v79, -v79, v206, v205
	v_div_fmas_f32 v79, v79, v201, v206
	v_div_fixup_f32 v66, v79, v66, 1.0
	v_cndmask_b32_e64 v79, v43, v42, s[6:7]
	v_cndmask_b32_e64 v79, v79, v40, s[8:9]
	v_add_f32_e32 v75, v75, v79
	v_mul_f32_e32 v75, 0xbfb8aa3b, v75
	v_exp_f32_e32 v75, v75
	v_mul_f32_e32 v66, 0xbf1b459e, v66
	v_mul_f32_e32 v66, 0x3fb8aa3b, v66
	v_exp_f32_e32 v66, v66
	v_add_f32_e32 v75, 1.0, v75
	v_div_scale_f32 v79, s[0:1], v75, v75, 1.0
	v_rcp_f32_e32 v201, v79
; DEVINL void rw_prep_unit(const Params& p, int unit) {
;     ...
;         const int t = tok0 + mt * 16 + 4 * g + jo;
;         const int s = t & (S_ - 1), b = t >> 12;
;         const unsigned c0 = (unsigned)(head * 64 + l15 * 4 + zo);
;         const unsigned rowo = (unsigned)t * (unsigned)(NCP * 2) + (unsigned)(C_RW * 2) + c0 * 2u;
;         float pr[4], pkr[4], pv[4];
;         rw_shift4(colsb, *(const float4*)(p.rw_mu + c0), rowo, s, pr);
;         rw_shift4(colsb, *(const float4*)(p.rw_mu + 1024u + c0), rowo + 2048u, s, pkr);
;         rw_shift4(colsb, *(const float4*)(p.rw_mu + 2048u + c0), rowo + 4096u, s, pv);
;         const float4 a0q = *(const float4*)(p.rw_a0 + c0), kkq = *(const float4*)(p.rw_k_k + c0);
;         const float4 kaq = *(const float4*)(p.rw_k_a + c0), rkq = *(const float4*)(p.rw_r_k + c0);
;         const float4 w0fq = *(const float4*)(p.rw_w0_f + c0), w0bq = *(const float4*)(p.rw_w0_b + c0);
;         const float a0v[4] = {a0q.x, a0q.y, a0q.z, a0q.w}, kkp[4] = {kkq.x, kkq.y, kkq.z, kkq.w};
;         const float kap[4] = {kaq.x, kaq.y, kaq.z, kaq.w}, rkp[4] = {rkq.x, rkq.y, rkq.z, rkq.w};
;         const float w0f[4] = {w0fq.x, w0fq.y, w0fq.z, w0fq.w}, w0b[4] = {w0bq.x, w0bq.y, w0bq.z, w0bq.w};
;     ...
;         char* rb = ws + O_REC + (reco + (unsigned)l15 * 64u);
;         *(uint4*)(rb) = make_uint4(hwf[0] | (hwf[1] << 16), hwf[2] | (hwf[3] << 16), hwb[0] | (hwb[1] << 16), hwb[2] | (hwb[3] << 16));
;         *(uint4*)(rb + 16) = make_uint4(ha[0] | (ha[1] << 16), ha[2] | (ha[3] << 16), hb[0] | (hb[1] << 16), hb[2] | (hb[3] << 16));
;         *(uint4*)(rb + 32) = make_uint4(hk[0] | (hk[1] << 16), hk[2] | (hk[3] << 16), hr[0] | (hr[1] << 16), hr[2] | (hr[3] << 16));
;         *(uint2*)(rb + 48) = make_uint2(hv[0] | (hv[1] << 16), hv[2] | (hv[3] << 16));
;         *(uint2*)(ws + O_GRW + tco) = make_uint2(bg[0] | (bg[1] << 16), bg[2] | (bg[3] << 16));
;         *(uint2*)(ws + O_BONUS + tco) = make_uint2(bbn[0] | (bbn[1] << 16), bbn[2] | (bbn[3] << 16));
	v_cvt_f16_f32_sdwa v66, v66 dst_sel:WORD_1 dst_unused:UNUSED_PAD src0_sel:DWORD
	v_fma_f32 v205, -v79, v201, 1.0
	v_fmac_f32_e32 v201, v205, v201
	v_div_scale_f32 v205, vcc, 1.0, v75, 1.0
	v_mul_f32_e32 v206, v205, v201
	v_fma_f32 v207, -v79, v206, v205
	v_fmac_f32_e32 v206, v207, v201
	v_fma_f32 v79, -v79, v206, v205
	v_div_fmas_f32 v79, v79, v201, v206
	v_div_fixup_f32 v75, v79, v75, 1.0
	v_mul_f32_e32 v75, 0xbf1b459e, v75
	v_mul_f32_e32 v75, 0x3fb8aa3b, v75
	v_exp_f32_e32 v75, v75
	v_mul_f32_e32 v79, v91, v83
	v_cvt_f16_f32_sdwa v83, -v79 dst_sel:WORD_1 dst_unused:UNUSED_PAD src0_sel:DWORD
	v_fma_mixlo_f16 v79, v82, v79, 0
	v_cvt_f16_f32_sdwa v75, v75 dst_sel:WORD_1 dst_unused:UNUSED_PAD src0_sel:DWORD
	v_fma_mixlo_f16 v82, v196, v87, 0
	v_fma_mixlo_f16 v87, v67, v195, v96
	v_cndmask_b32_e64 v67, v63, v62, s[6:7]
	v_cndmask_b32_e64 v67, v67, v60, s[8:9]
	v_cvt_pk_bf16_f32 v91, v67, s0
	v_mul_f32_e32 v67, v200, v80
	v_cvt_pk_bf16_f32 v80, v67, s0
	v_add_lshl_u32 v67, v94, v191, 22
	v_or3_b32 v95, v67, v95, v186
	v_or_b32_e32 v65, v66, v65
	v_or_b32_e32 v67, v75, v74
	v_or_b32_e32 v66, v73, v72
	global_store_dwordx4 v95, v[64:67], s[36:37] nt
	v_lshlrev_b32_e32 v72, 16, v77
	v_lshl_add_u32 v94, v194, 11, v178
	v_lshlrev_b32_e32 v66, 16, v79
	v_or_b32_e32 v65, v83, v90
	v_or_b32_e32 v64, v89, v212
	v_or_b32_sdwa v67, v66, v78 dst_sel:DWORD dst_unused:UNUSED_PAD src0_sel:DWORD src1_sel:WORD_0
	v_or_b32_sdwa v66, v72, v88 dst_sel:DWORD dst_unused:UNUSED_PAD src0_sel:DWORD src1_sel:WORD_0
	global_store_dwordx4 v95, v[64:67], s[36:37] offset:256 nt
	v_lshlrev_b32_e32 v72, 16, v93
	s_add_i32 s6, s40, 1
	v_lshlrev_b32_e32 v64, 16, v82
	v_lshlrev_b32_e32 v66, 16, v85
	v_lshlrev_b32_e32 v67, 16, v87
	v_or_b32_sdwa v65, v64, v81 dst_sel:DWORD dst_unused:UNUSED_PAD src0_sel:DWORD src1_sel:WORD_0
	v_or_b32_sdwa v64, v66, v84 dst_sel:DWORD dst_unused:UNUSED_PAD src0_sel:DWORD src1_sel:WORD_0
	v_or_b32_sdwa v67, v67, v86 dst_sel:DWORD dst_unused:UNUSED_PAD src0_sel:DWORD src1_sel:WORD_0
	v_or_b32_sdwa v66, v72, v92 dst_sel:DWORD dst_unused:UNUSED_PAD src0_sel:DWORD src1_sel:WORD_0
	global_store_dwordx4 v95, v[64:67], s[36:37] offset:512 nt
	s_cmp_eq_u32 s6, 1
	s_nop 0
	v_lshlrev_b32_e32 v64, 16, v71
	v_lshlrev_b32_e32 v66, 16, v69
	v_or_b32_sdwa v65, v64, v70 dst_sel:DWORD dst_unused:UNUSED_PAD src0_sel:DWORD src1_sel:WORD_0
	v_or_b32_sdwa v64, v66, v68 dst_sel:DWORD dst_unused:UNUSED_PAD src0_sel:DWORD src1_sel:WORD_0
	global_store_dwordx2 v95, v[64:65], s[36:37] offset:768 nt
	v_lshlrev_b32_e32 v64, 16, v91
	v_lshlrev_b32_e32 v66, 16, v203
	v_or_b32_sdwa v65, v64, v197 dst_sel:DWORD dst_unused:UNUSED_PAD src0_sel:DWORD src1_sel:WORD_0
	v_or_b32_sdwa v64, v66, v209 dst_sel:DWORD dst_unused:UNUSED_PAD src0_sel:DWORD src1_sel:WORD_0
	global_store_dwordx2 v94, v[64:65], s[38:39] nt
	v_lshlrev_b32_e32 v64, 16, v80
	v_lshlrev_b32_e32 v66, 16, v204
	v_or_b32_sdwa v65, v64, v198 dst_sel:DWORD dst_unused:UNUSED_PAD src0_sel:DWORD src1_sel:WORD_0
	v_or_b32_sdwa v64, v66, v210 dst_sel:DWORD dst_unused:UNUSED_PAD src0_sel:DWORD src1_sel:WORD_0
	global_store_dwordx2 v94, v[64:65], s[70:71] nt
	v_mov_b32_e32 v64, s6
	v_mov_b32_e32 v65, v97
	s_cselect_b64 s[6:7], -1, 0
	v_add_u32_e32 v96, v65, v192
	v_add_u32_e32 v194, v193, v64
	v_lshlrev_b32_e32 v178, 1, v96
	v_and_b32_e32 v212, 0xfff, v194
	v_mad_u64_u32 v[72:73], s[0:1], v194, s49, v[178:179]
	v_add_u32_e32 v68, 0x1840, v72
	v_lshlrev_b64 v[74:75], 2, v[96:97]
	v_cmp_eq_u32_e32 vcc, 0, v212
	v_add_u32_e32 v69, 0xffffc440, v72
	s_nop 0
	v_cndmask_b32_e32 v70, v69, v68, vcc
	v_cmp_eq_u32_e64 s[0:1], s44, v212
	v_add_u32_e32 v69, 0x6c40, v72
	ds_read_b128 v[64:67], v74 offset:21504
	v_cndmask_b32_e64 v73, v69, v68, s[0:1]
	global_load_dwordx2 v[68:69], v68, s[18:19]
	s_nop 0
	global_load_dwordx2 v[70:71], v70, s[18:19]
	s_nop 0
	global_load_dwordx2 v[76:77], v73, s[18:19]
	v_cndmask_b32_e64 v223, v11, v9, s[6:7]
	s_add_i32 s40, s40, 2
	s_cmp_eq_u32 s40, 4
	s_waitcnt vmcnt(2) lgkmcnt(0)
	v_lshlrev_b32_e32 v209, 16, v68
	s_waitcnt vmcnt(1)
	v_cndmask_b32_e64 v70, v70, 0, vcc
	s_waitcnt vmcnt(0)
	v_cndmask_b32_e64 v73, v76, 0, s[0:1]
	v_cndmask_b32_e64 v76, v77, 0, s[0:1]
	v_and_b32_e32 v203, 0xffff0000, v68
	v_lshlrev_b32_e32 v68, 16, v70
	v_lshlrev_b32_e32 v77, 16, v73
	v_cndmask_b32_e64 v71, v71, 0, vcc
	v_lshlrev_b32_e32 v197, 16, v69
	v_and_b32_e32 v96, 0xffff0000, v69
	v_and_b32_e32 v69, 0xffff0000, v70
	v_and_b32_e32 v73, 0xffff0000, v73
	v_add_f32_e32 v68, v68, v77
	v_lshlrev_b32_e32 v70, 16, v71
	v_lshlrev_b32_e32 v78, 16, v76
	v_fma_f32 v210, v68, 0.5, -v209
	v_add_f32_e32 v68, v69, v73
	v_and_b32_e32 v71, 0xffff0000, v71
	v_and_b32_e32 v76, 0xffff0000, v76
	v_fma_f32 v204, v68, 0.5, -v203
	v_add_f32_e32 v68, v70, v78
	v_fma_f32 v198, v68, 0.5, -v197
	v_add_f32_e32 v68, v71, v76
	v_add_u32_e32 v73, 0x2040, v72
	v_add_u32_e32 v76, 0xffffcc40, v72
	v_cndmask_b32_e32 v78, v76, v73, vcc
	v_add_u32_e32 v76, 0x7440, v72
	v_fma_f32 v195, v68, 0.5, -v96
	s_nop 0
	v_cndmask_b32_e64 v80, v76, v73, s[0:1]
	ds_read_b128 v[68:71], v74 offset:25600
	s_nop 0
	global_load_dwordx2 v[76:77], v73, s[18:19]
	s_nop 0
	global_load_dwordx2 v[78:79], v78, s[18:19]
	s_nop 0
	global_load_dwordx2 v[80:81], v80, s[18:19]
	v_fma_f32 v222, v64, v210, v209
	v_fma_f32 v221, v65, v204, v203
	v_fma_f32 v220, v66, v198, v197
	v_fma_f32 v219, v67, v195, v96
	s_waitcnt vmcnt(2) lgkmcnt(0)
	v_lshlrev_b32_e32 v214, 16, v76
	s_waitcnt vmcnt(1)
	v_cndmask_b32_e64 v73, v78, 0, vcc
	v_cndmask_b32_e64 v78, v79, 0, vcc
	s_waitcnt vmcnt(0)
; DEVINL float sigm(float x) { return 1.f / (1.f + __expf(-x)); }
; DEVINL void rw_prep_unit(const Params& p, int unit) {
;     ...
;         const int t = tok0 + mt * 16 + 4 * g + jo;
;         const int s = t & (S_ - 1), b = t >> 12;
;         const unsigned c0 = (unsigned)(head * 64 + l15 * 4 + zo);
;         const unsigned rowo = (unsigned)t * (unsigned)(NCP * 2) + (unsigned)(C_RW * 2) + c0 * 2u;
;         float pr[4], pkr[4], pv[4];
;         rw_shift4(colsb, *(const float4*)(p.rw_mu + c0), rowo, s, pr);
;         rw_shift4(colsb, *(const float4*)(p.rw_mu + 1024u + c0), rowo + 2048u, s, pkr);
;         rw_shift4(colsb, *(const float4*)(p.rw_mu + 2048u + c0), rowo + 4096u, s, pv);
;         const float4 a0q = *(const float4*)(p.rw_a0 + c0), kkq = *(const float4*)(p.rw_k_k + c0);
;         const float4 kaq = *(const float4*)(p.rw_k_a + c0), rkq = *(const float4*)(p.rw_r_k + c0);
;         const float4 w0fq = *(const float4*)(p.rw_w0_f + c0), w0bq = *(const float4*)(p.rw_w0_b + c0);
;         const float a0v[4] = {a0q.x, a0q.y, a0q.z, a0q.w}, kkp[4] = {kkq.x, kkq.y, kkq.z, kkq.w};
;         const float kap[4] = {kaq.x, kaq.y, kaq.z, kaq.w}, rkp[4] = {rkq.x, rkq.y, rkq.z, rkq.w};
;         const float w0f[4] = {w0fq.x, w0fq.y, w0fq.z, w0fq.w}, w0b[4] = {w0bq.x, w0bq.y, w0bq.z, w0bq.w};
;         float pk[4], av[4], kkv[4];
;         float n2 = 0.f, dot = 0.f;
; #pragma unroll
;         for (int n = 0; n < 4; ++n) {
;           const float kraw = pkr[n];
;           float a = sigm(a0v[n] + sel4(aa[n], j));
;           av[n] = a;
;           float kk = kraw * kkp[n];
;           kkv[n] = kk;
;           n2 += kk * kk;
;           float k2 = kraw * (1.f + (a - 1.f) * kap[n]);
;           pk[n] = k2;
;           dot += pr[n] * k2 * rkp[n];
;         }
	v_cndmask_b32_e64 v79, v80, 0, s[0:1]
	v_cndmask_b32_e64 v80, v81, 0, s[0:1]
	v_and_b32_e32 v206, 0xffff0000, v76
	v_lshlrev_b32_e32 v76, 16, v73
	v_lshlrev_b32_e32 v81, 16, v79
	v_add_f32_e32 v76, v76, v81
	v_and_b32_e32 v73, 0xffff0000, v73
	v_and_b32_e32 v79, 0xffff0000, v79
	v_fma_f32 v76, v76, 0.5, -v214
	v_fmac_f32_e32 v214, v68, v76
	v_add_f32_e32 v68, v73, v79
	v_lshlrev_b32_e32 v200, 16, v77
	v_and_b32_e32 v196, 0xffff0000, v77
	v_lshlrev_b32_e32 v77, 16, v78
	v_lshlrev_b32_e32 v82, 16, v80
	v_fma_f32 v68, v68, 0.5, -v206
	v_fmac_f32_e32 v206, v69, v68
	v_add_f32_e32 v68, v77, v82
	v_and_b32_e32 v78, 0xffff0000, v78
	v_and_b32_e32 v80, 0xffff0000, v80
	v_fma_f32 v68, v68, 0.5, -v200
	v_fmac_f32_e32 v200, v70, v68
	v_add_f32_e32 v68, v78, v80
	v_fma_f32 v68, v68, 0.5, -v196
	v_add_u32_e32 v73, 0x2840, v72
	v_add_u32_e32 v76, 0xffffd440, v72
	v_add_u32_e32 v72, 0x7c40, v72
	v_fmac_f32_e32 v196, v71, v68
	s_nop 0
	v_cndmask_b32_e32 v76, v76, v73, vcc
	v_cndmask_b32_e64 v78, v72, v73, s[0:1]
	ds_read_b128 v[68:71], v74 offset:29696
	s_nop 0
	global_load_dwordx2 v[72:73], v73, s[18:19]
	s_nop 0
	global_load_dwordx2 v[76:77], v76, s[18:19]
	s_nop 0
	global_load_dwordx2 v[78:79], v78, s[18:19]
	s_waitcnt vmcnt(2) lgkmcnt(0)
	v_lshlrev_b32_e32 v216, 16, v72
	s_waitcnt vmcnt(1)
	v_cndmask_b32_e64 v76, v76, 0, vcc
	s_waitcnt vmcnt(0)
	v_cndmask_b32_e64 v78, v78, 0, s[0:1]
	v_and_b32_e32 v211, 0xffff0000, v72
	v_lshlrev_b32_e32 v72, 16, v76
	v_lshlrev_b32_e32 v80, 16, v78
	v_cndmask_b32_e64 v77, v77, 0, vcc
	v_cndmask_b32_e64 v79, v79, 0, s[0:1]
	v_lshlrev_b32_e32 v205, 16, v73
	v_and_b32_e32 v199, 0xffff0000, v73
	v_and_b32_e32 v73, 0xffff0000, v76
	v_and_b32_e32 v78, 0xffff0000, v78
	v_add_f32_e32 v72, v72, v80
	v_lshlrev_b32_e32 v76, 16, v77
	v_lshlrev_b32_e32 v81, 16, v79
	v_fma_f32 v218, v72, 0.5, -v216
	v_add_f32_e32 v72, v73, v78
	v_and_b32_e32 v77, 0xffff0000, v77
	v_and_b32_e32 v79, 0xffff0000, v79
	v_fma_f32 v215, v72, 0.5, -v211
	v_add_f32_e32 v72, v76, v81
	v_fma_f32 v208, v72, 0.5, -v205
	v_add_f32_e32 v72, v77, v79
	v_fma_f32 v202, v72, 0.5, -v199
	s_nop 0
	ds_read_b128 v[92:95], v74 offset:33792
	s_nop 0
	ds_read_b128 v[88:91], v74 offset:37888
	s_nop 0
	ds_read_b128 v[84:87], v74 offset:41984
	s_nop 0
	ds_read_b128 v[80:83], v74 offset:46080
	s_nop 0
	ds_read_b128 v[76:79], v74 offset:50176
	s_nop 0
	ds_read_b128 v[72:75], v74 offset:54272
	v_fma_f32 v217, v68, v218, v216
	v_fma_mixlo_f16 v68, v68, v218, v216
	v_fma_f32 v213, v69, v215, v211
	v_fma_mixlo_f16 v69, v69, v215, v211
	v_fma_f32 v207, v70, v208, v205
	v_fma_mixlo_f16 v70, v70, v208, v205
	v_fma_f32 v201, v71, v202, v199
	v_fma_mixlo_f16 v71, v71, v202, v199
	s_waitcnt lgkmcnt(5)
	v_add_f32_e32 v92, v92, v223
	v_mul_f32_e32 v92, 0xbfb8aa3b, v92
	v_exp_f32_e32 v92, v92
	s_waitcnt lgkmcnt(4)
	v_mul_f32_e32 v89, v206, v89
	v_mul_f32_e32 v88, v214, v88
	v_mul_f32_e32 v90, v200, v90
	v_add_f32_e32 v92, 1.0, v92
	v_div_scale_f32 v223, s[0:1], v92, v92, 1.0
	v_rcp_f32_e32 v224, v223
	v_mul_f32_e32 v91, v196, v91
	v_fma_f32 v225, -v223, v224, 1.0
	v_fmac_f32_e32 v224, v225, v224
	v_div_scale_f32 v225, vcc, 1.0, v92, 1.0
	v_mul_f32_e32 v226, v225, v224
	v_fma_f32 v227, -v223, v226, v225
	v_fmac_f32_e32 v226, v227, v224
	v_fma_f32 v223, -v223, v226, v225
	v_div_fmas_f32 v223, v223, v224, v226
	v_div_fixup_f32 v92, v223, v92, 1.0
	v_add_f32_e32 v223, -1.0, v92
	s_waitcnt lgkmcnt(3)
	v_fma_f32 v84, v84, v223, 1.0
	v_mul_f32_e32 v223, v214, v84
	v_mul_f32_e32 v222, v222, v223
	s_waitcnt lgkmcnt(2)
	v_fma_f32 v80, v80, v222, 0
	v_cndmask_b32_e64 v222, v23, v21, s[6:7]
	v_add_f32_e32 v93, v93, v222
	v_mul_f32_e32 v93, 0xbfb8aa3b, v93
	v_exp_f32_e32 v93, v93
	v_fma_mixlo_f16 v84, v214, v84, 0
	v_add_f32_e32 v93, 1.0, v93
	v_div_scale_f32 v222, s[0:1], v93, v93, 1.0
	v_rcp_f32_e32 v223, v222
	s_nop 0
	v_fma_f32 v224, -v222, v223, 1.0
	v_fmac_f32_e32 v223, v224, v223
	v_div_scale_f32 v224, vcc, 1.0, v93, 1.0
	v_mul_f32_e32 v225, v224, v223
	v_fma_f32 v226, -v222, v225, v224
	v_fmac_f32_e32 v225, v226, v223
	v_fma_f32 v222, -v222, v225, v224
	v_div_fmas_f32 v222, v222, v223, v225
	v_div_fixup_f32 v93, v222, v93, 1.0
	v_add_f32_e32 v223, -1.0, v93
	v_fma_f32 v85, v85, v223, 1.0
	v_mul_f32_e32 v223, v206, v85
	v_mul_f32_e32 v221, v221, v223
	v_fmac_f32_e32 v80, v81, v221
	v_cndmask_b32_e64 v81, v35, v33, s[6:7]
	v_add_f32_e32 v81, v94, v81
	v_mul_f32_e32 v81, 0xbfb8aa3b, v81
	v_exp_f32_e32 v81, v81
	v_mul_f32_e32 v222, v89, v89
	v_fmac_f32_e32 v222, v88, v88
	v_fmac_f32_e32 v222, v90, v90
	v_add_f32_e32 v81, 1.0, v81
	v_div_scale_f32 v94, s[0:1], v81, v81, 1.0
	v_rcp_f32_e32 v221, v94
	v_fmac_f32_e32 v222, v91, v91
	v_fma_mixlo_f16 v85, v206, v85, 0
	v_fma_f32 v223, -v94, v221, 1.0
	v_fmac_f32_e32 v221, v223, v221
	v_div_scale_f32 v223, vcc, 1.0, v81, 1.0
	v_mul_f32_e32 v224, v223, v221
	v_fma_f32 v225, -v94, v224, v223
	v_fmac_f32_e32 v224, v225, v221
	v_fma_f32 v94, -v94, v224, v223
	v_div_fmas_f32 v94, v94, v221, v224
	v_div_fixup_f32 v81, v94, v81, 1.0
	v_add_f32_e32 v94, -1.0, v81
	v_fma_f32 v86, v86, v94, 1.0
	v_mul_f32_e32 v94, v200, v86
	v_mul_f32_e32 v94, v220, v94
	v_fmac_f32_e32 v80, v82, v94
	v_cndmask_b32_e64 v82, v47, v45, s[6:7]
	v_add_f32_e32 v82, v95, v82
	v_mul_f32_e32 v82, 0xbfb8aa3b, v82
	v_exp_f32_e32 v82, v82
	s_nop 0
	v_add_f32_e32 v82, 1.0, v82
	v_div_scale_f32 v94, s[0:1], v82, v82, 1.0
	v_rcp_f32_e32 v95, v94
	s_nop 0
	v_fma_f32 v220, -v94, v95, 1.0
	v_fmac_f32_e32 v95, v220, v95
	v_div_scale_f32 v220, vcc, 1.0, v82, 1.0
	v_mul_f32_e32 v221, v220, v95
	v_fma_f32 v223, -v94, v221, v220
	v_fmac_f32_e32 v221, v223, v95
	v_fma_f32 v94, -v94, v221, v220
; DEVINL u16 f2bf(float a) { return (u16)(pk2(a, 0.f) & 0xffffu); }
; DEVINL float sigm(float x) { return 1.f / (1.f + __expf(-x)); }
; DEVINL void rw_prep_unit(const Params& p, int unit) {
;     ...
;         n2 = allred16(n2);
;         dot = allred16(dot);
;         const float inv = 1.f / fmaxf(sqrtf(n2), 1e-12f);
;         const unsigned reco = ((unsigned)((b * 16 + head) * 4096 + s)) * 1024u;
;         const unsigned tco = (unsigned)t * 2048u + c0 * 2u;
;         unsigned hwf[4], hwb[4], ha[4], hb[4], hk[4], hr[4], hv[4], bg[4], bbn[4];
; #pragma unroll
;         for (int n = 0; n < 4; ++n) {
;           float wf = __expf(-0.606531f * sigm(w0f[n] + sel4(awf[n], j)));
;           float wb = __expf(-0.606531f * sigm(w0b[n] + sel4(awb[n], j)));
;           float kkn = kkv[n] * inv;
;           hwf[n] = f2h(wf); hwb[n] = f2h(wb); ha[n] = f2h(-kkn); hb[n] = f2h(kkn * av[n]);
;           hk[n] = f2h(pk[n]); hr[n] = f2h(pr[n]); hv[n] = f2h(pv[n]);
;           bg[n] = f2bf(sel4(ag[n], j)); bbn[n] = f2bf(dot * pv[n]);
;         }
	v_div_fmas_f32 v94, v94, v95, v221
	v_div_fixup_f32 v82, v94, v82, 1.0
	v_add_f32_e32 v94, -1.0, v82
	v_fma_f32 v87, v87, v94, 1.0
	v_mul_f32_e32 v94, v196, v87
	v_mul_f32_e32 v94, v219, v94
	v_fmac_f32_e32 v80, v83, v94
	v_add_f32_dpp v83, v222, v222 quad_perm:[1,0,3,2] row_mask:0xf bank_mask:0xf bound_ctrl:1
	s_nop 0
	v_add_f32_dpp v80, v80, v80 quad_perm:[1,0,3,2] row_mask:0xf bank_mask:0xf bound_ctrl:1
	v_add_f32_dpp v83, v83, v83 quad_perm:[2,3,0,1] row_mask:0xf bank_mask:0xf bound_ctrl:1
	s_nop 0
	v_add_f32_dpp v80, v80, v80 quad_perm:[2,3,0,1] row_mask:0xf bank_mask:0xf bound_ctrl:1
	v_add_f32_dpp v83, v83, v83 row_half_mirror row_mask:0xf bank_mask:0xf bound_ctrl:1
	s_nop 0
	v_add_f32_dpp v80, v80, v80 row_half_mirror row_mask:0xf bank_mask:0xf bound_ctrl:1
	v_add_f32_dpp v83, v83, v83 row_mirror row_mask:0xf bank_mask:0xf bound_ctrl:1
	v_cmp_gt_f32_e32 vcc, s50, v83
	v_mul_f32_e32 v94, 0x4f800000, v83
	v_add_f32_dpp v80, v80, v80 row_mirror row_mask:0xf bank_mask:0xf bound_ctrl:1
	v_cndmask_b32_e32 v83, v83, v94, vcc
	v_sqrt_f32_e32 v94, v83
	s_nop 0
	v_add_u32_e32 v95, -1, v94
	v_fma_f32 v219, -v95, v94, v83
	v_cmp_ge_f32_e64 s[0:1], 0, v219
	v_add_u32_e32 v219, 1, v94
	s_nop 0
	v_cndmask_b32_e64 v95, v94, v95, s[0:1]
	v_fma_f32 v94, -v219, v94, v83
	v_cmp_lt_f32_e64 s[0:1], 0, v94
	s_nop 1
	v_cndmask_b32_e64 v94, v95, v219, s[0:1]
	v_mul_f32_e32 v95, 0x37800000, v94
	v_cndmask_b32_e32 v94, v94, v95, vcc
	v_cmp_class_f32_e32 vcc, v83, v179
	s_nop 1
	v_cndmask_b32_e32 v83, v94, v83, vcc
	v_max_f32_e32 v83, 0x2b8cbccc, v83
	v_div_scale_f32 v94, s[0:1], v83, v83, 1.0
	v_rcp_f32_e32 v95, v94
	s_nop 0
	v_fma_f32 v219, -v94, v95, 1.0
	v_fmac_f32_e32 v95, v219, v95
	v_div_scale_f32 v219, vcc, 1.0, v83, 1.0
	v_mul_f32_e32 v220, v219, v95
	v_fma_f32 v221, -v94, v220, v219
	v_fmac_f32_e32 v220, v221, v95
	v_fma_f32 v94, -v94, v220, v219
	v_div_fmas_f32 v94, v94, v95, v220
	v_lshlrev_b32_e32 v95, 10, v212
	v_cndmask_b32_e64 v212, v3, v1, s[6:7]
	s_waitcnt lgkmcnt(1)
	v_add_f32_e32 v76, v76, v212
	v_mul_f32_e32 v76, 0xbfb8aa3b, v76
	v_exp_f32_e32 v76, v76
	v_div_fixup_f32 v83, v94, v83, 1.0
	v_mul_f32_e32 v88, v88, v83
	v_lshrrev_b32_e32 v94, 8, v194
	v_add_f32_e32 v76, 1.0, v76
	v_div_scale_f32 v212, s[0:1], v76, v76, 1.0
	v_rcp_f32_e32 v219, v212
	v_and_b32_e32 v94, 0x3f0, v94
	v_fma_f32 v220, -v212, v219, 1.0
	v_fmac_f32_e32 v219, v220, v219
	v_div_scale_f32 v220, vcc, 1.0, v76, 1.0
	v_mul_f32_e32 v221, v220, v219
	v_fma_f32 v222, -v212, v221, v220
	v_fmac_f32_e32 v221, v222, v219
	v_fma_f32 v212, -v212, v221, v220
	v_div_fmas_f32 v212, v212, v219, v221
	v_div_fixup_f32 v76, v212, v76, 1.0
	v_cndmask_b32_e64 v212, v7, v5, s[6:7]
	s_waitcnt lgkmcnt(0)
	v_add_f32_e32 v72, v72, v212
	v_mul_f32_e32 v72, 0xbfb8aa3b, v72
	v_exp_f32_e32 v72, v72
	v_mul_f32_e32 v76, 0xbf1b459e, v76
	v_mul_f32_e32 v76, 0x3fb8aa3b, v76
	v_exp_f32_e32 v76, v76
	v_add_f32_e32 v72, 1.0, v72
	v_div_scale_f32 v212, s[0:1], v72, v72, 1.0
	v_rcp_f32_e32 v219, v212
	v_cvt_f16_f32_e32 v76, v76
	v_fma_f32 v220, -v212, v219, 1.0
	v_fmac_f32_e32 v219, v220, v219
	v_div_scale_f32 v220, vcc, 1.0, v72, 1.0
	v_mul_f32_e32 v221, v220, v219
	v_fma_f32 v222, -v212, v221, v220
	v_fmac_f32_e32 v221, v222, v219
	v_fma_f32 v212, -v212, v221, v220
	v_div_fmas_f32 v212, v212, v219, v221
	v_div_fixup_f32 v72, v212, v72, 1.0
	v_cvt_f16_f32_e64 v212, -v88
	v_fma_mixlo_f16 v88, v92, v88, 0
	v_fma_mixlo_f16 v92, v64, v210, v209
	v_cndmask_b32_e64 v64, v51, v49, s[6:7]
	v_cvt_pk_bf16_f32 v209, v64, s0
	v_mul_f32_e32 v64, v217, v80
	v_cvt_pk_bf16_f32 v210, v64, s0
	v_cndmask_b32_e64 v64, v15, v13, s[6:7]
	v_add_f32_e32 v64, v77, v64
	v_mul_f32_e32 v64, 0xbfb8aa3b, v64
	v_exp_f32_e32 v64, v64
	v_mul_f32_e32 v72, 0xbf1b459e, v72
	v_mul_f32_e32 v72, 0x3fb8aa3b, v72
	v_exp_f32_e32 v72, v72
	v_add_f32_e32 v64, 1.0, v64
	v_div_scale_f32 v77, s[0:1], v64, v64, 1.0
	v_rcp_f32_e32 v214, v77
	v_cvt_f16_f32_e32 v72, v72
	v_fma_f32 v216, -v77, v214, 1.0
	v_fmac_f32_e32 v214, v216, v214
	v_div_scale_f32 v216, vcc, 1.0, v64, 1.0
	v_mul_f32_e32 v217, v216, v214
	v_fma_f32 v218, -v77, v217, v216
	v_fmac_f32_e32 v217, v218, v214
	v_fma_f32 v77, -v77, v217, v216
	v_div_fmas_f32 v77, v77, v214, v217
	v_div_fixup_f32 v64, v77, v64, 1.0
	v_cndmask_b32_e64 v77, v19, v17, s[6:7]
	v_add_f32_e32 v73, v73, v77
	v_mul_f32_e32 v73, 0xbfb8aa3b, v73
	v_exp_f32_e32 v73, v73
	v_mul_f32_e32 v64, 0xbf1b459e, v64
	v_mul_f32_e32 v64, 0x3fb8aa3b, v64
	v_exp_f32_e32 v64, v64
	v_add_f32_e32 v73, 1.0, v73
	v_div_scale_f32 v77, s[0:1], v73, v73, 1.0
	v_rcp_f32_e32 v214, v77
	v_cvt_f16_f32_sdwa v64, v64 dst_sel:WORD_1 dst_unused:UNUSED_PAD src0_sel:DWORD
	v_fma_f32 v216, -v77, v214, 1.0
	v_fmac_f32_e32 v214, v216, v214
	v_div_scale_f32 v216, vcc, 1.0, v73, 1.0
	v_mul_f32_e32 v217, v216, v214
	v_fma_f32 v218, -v77, v217, v216
	v_fmac_f32_e32 v217, v218, v214
	v_fma_f32 v77, -v77, v217, v216
	v_div_fmas_f32 v77, v77, v214, v217
	v_div_fixup_f32 v73, v77, v73, 1.0
	v_mul_f32_e32 v77, v89, v83
	v_cvt_f16_f32_sdwa v89, -v77 dst_sel:WORD_1 dst_unused:UNUSED_PAD src0_sel:DWORD
	v_fma_mixlo_f16 v77, v93, v77, 0
	v_fma_mixlo_f16 v93, v65, v204, v203
	v_cndmask_b32_e64 v65, v55, v53, s[6:7]
	v_cvt_pk_bf16_f32 v203, v65, s0
	v_mul_f32_e32 v65, v213, v80
	v_cvt_pk_bf16_f32 v204, v65, s0
	v_cndmask_b32_e64 v65, v27, v25, s[6:7]
	v_add_f32_e32 v65, v78, v65
	v_mul_f32_e32 v65, 0xbfb8aa3b, v65
	v_exp_f32_e32 v65, v65
	v_mul_f32_e32 v73, 0xbf1b459e, v73
	v_mul_f32_e32 v73, 0x3fb8aa3b, v73
	v_exp_f32_e32 v73, v73
	v_add_f32_e32 v65, 1.0, v65
	v_div_scale_f32 v78, s[0:1], v65, v65, 1.0
	v_rcp_f32_e32 v206, v78
; DEVINL u16 f2bf(float a) { return (u16)(pk2(a, 0.f) & 0xffffu); }
; DEVINL float sigm(float x) { return 1.f / (1.f + __expf(-x)); }
; DEVINL void rw_prep_unit(const Params& p, int unit) {
;     ...
; #pragma unroll
;         for (int n = 0; n < 4; ++n) {
;           float wf = __expf(-0.606531f * sigm(w0f[n] + sel4(awf[n], j)));
;           float wb = __expf(-0.606531f * sigm(w0b[n] + sel4(awb[n], j)));
;           float kkn = kkv[n] * inv;
;           hwf[n] = f2h(wf); hwb[n] = f2h(wb); ha[n] = f2h(-kkn); hb[n] = f2h(kkn * av[n]);
;           hk[n] = f2h(pk[n]); hr[n] = f2h(pr[n]); hv[n] = f2h(pv[n]);
;           bg[n] = f2bf(sel4(ag[n], j)); bbn[n] = f2bf(dot * pv[n]);
;         }
;         char* rb = ws + O_REC + (reco + (unsigned)l15 * 64u);
;         *(uint4*)(rb) = make_uint4(hwf[0] | (hwf[1] << 16), hwf[2] | (hwf[3] << 16), hwb[0] | (hwb[1] << 16), hwb[2] | (hwb[3] << 16));
;         *(uint4*)(rb + 16) = make_uint4(ha[0] | (ha[1] << 16), ha[2] | (ha[3] << 16), hb[0] | (hb[1] << 16), hb[2] | (hb[3] << 16));
;         *(uint4*)(rb + 32) = make_uint4(hk[0] | (hk[1] << 16), hk[2] | (hk[3] << 16), hr[0] | (hr[1] << 16), hr[2] | (hr[3] << 16));
;         *(uint2*)(rb + 48) = make_uint2(hv[0] | (hv[1] << 16), hv[2] | (hv[3] << 16));
;         *(uint2*)(ws + O_GRW + tco) = make_uint2(bg[0] | (bg[1] << 16), bg[2] | (bg[3] << 16));
;         *(uint2*)(ws + O_BONUS + tco) = make_uint2(bbn[0] | (bbn[1] << 16), bbn[2] | (bbn[3] << 16));
;       }
	v_cvt_f16_f32_sdwa v73, v73 dst_sel:WORD_1 dst_unused:UNUSED_PAD src0_sel:DWORD
	v_or_b32_e32 v64, v64, v76
	v_fma_f32 v211, -v78, v206, 1.0
	v_fmac_f32_e32 v206, v211, v206
	v_div_scale_f32 v211, vcc, 1.0, v65, 1.0
	v_mul_f32_e32 v213, v211, v206
	v_fma_f32 v214, -v78, v213, v211
	v_fmac_f32_e32 v213, v214, v206
	v_fma_f32 v78, -v78, v213, v211
	v_div_fmas_f32 v78, v78, v206, v213
	v_div_fixup_f32 v65, v78, v65, 1.0
	v_cndmask_b32_e64 v78, v31, v29, s[6:7]
	v_add_f32_e32 v74, v74, v78
	v_mul_f32_e32 v74, 0xbfb8aa3b, v74
	v_exp_f32_e32 v74, v74
	v_mul_f32_e32 v65, 0xbf1b459e, v65
	v_mul_f32_e32 v65, 0x3fb8aa3b, v65
	v_exp_f32_e32 v65, v65
	v_add_f32_e32 v74, 1.0, v74
	v_div_scale_f32 v78, s[0:1], v74, v74, 1.0
	v_rcp_f32_e32 v206, v78
	v_cvt_f16_f32_e32 v65, v65
	v_fma_f32 v211, -v78, v206, 1.0
	v_fmac_f32_e32 v206, v211, v206
	v_div_scale_f32 v211, vcc, 1.0, v74, 1.0
	v_mul_f32_e32 v213, v211, v206
	v_fma_f32 v214, -v78, v213, v211
	v_fmac_f32_e32 v213, v214, v206
	v_fma_f32 v78, -v78, v213, v211
	v_div_fmas_f32 v78, v78, v206, v213
	v_div_fixup_f32 v74, v78, v74, 1.0
	v_mul_f32_e32 v78, v90, v83
	v_cvt_f16_f32_e64 v90, -v78
	v_fma_mixlo_f16 v78, v81, v78, 0
	v_fma_mixlo_f16 v81, v200, v86, 0
	v_fma_mixlo_f16 v86, v66, v198, v197
	v_cndmask_b32_e64 v66, v59, v57, s[6:7]
	v_cvt_pk_bf16_f32 v197, v66, s0
	v_mul_f32_e32 v66, v207, v80
	v_cvt_pk_bf16_f32 v198, v66, s0
	v_cndmask_b32_e64 v66, v39, v37, s[6:7]
	v_add_f32_e32 v66, v79, v66
	v_mul_f32_e32 v66, 0xbfb8aa3b, v66
	v_exp_f32_e32 v66, v66
	v_mul_f32_e32 v74, 0xbf1b459e, v74
	v_mul_f32_e32 v74, 0x3fb8aa3b, v74
	v_exp_f32_e32 v74, v74
	v_add_f32_e32 v66, 1.0, v66
	v_div_scale_f32 v79, s[0:1], v66, v66, 1.0
	v_rcp_f32_e32 v200, v79
	v_cvt_f16_f32_e32 v74, v74
	v_fma_f32 v205, -v79, v200, 1.0
	v_fmac_f32_e32 v200, v205, v200
	v_div_scale_f32 v205, vcc, 1.0, v66, 1.0
	v_mul_f32_e32 v206, v205, v200
	v_fma_f32 v207, -v79, v206, v205
	v_fmac_f32_e32 v206, v207, v200
	v_fma_f32 v79, -v79, v206, v205
	v_div_fmas_f32 v79, v79, v200, v206
	v_div_fixup_f32 v66, v79, v66, 1.0
	v_cndmask_b32_e64 v79, v43, v41, s[6:7]
	v_add_f32_e32 v75, v75, v79
	v_mul_f32_e32 v75, 0xbfb8aa3b, v75
	v_exp_f32_e32 v75, v75
	v_mul_f32_e32 v66, 0xbf1b459e, v66
	v_mul_f32_e32 v66, 0x3fb8aa3b, v66
	v_exp_f32_e32 v66, v66
	v_add_f32_e32 v75, 1.0, v75
	v_div_scale_f32 v79, s[0:1], v75, v75, 1.0
	v_rcp_f32_e32 v200, v79
	v_cvt_f16_f32_sdwa v66, v66 dst_sel:WORD_1 dst_unused:UNUSED_PAD src0_sel:DWORD
	v_fma_f32 v205, -v79, v200, 1.0
	v_fmac_f32_e32 v200, v205, v200
	v_div_scale_f32 v205, vcc, 1.0, v75, 1.0
	v_mul_f32_e32 v206, v205, v200
	v_fma_f32 v207, -v79, v206, v205
	v_fmac_f32_e32 v206, v207, v200
	v_fma_f32 v79, -v79, v206, v205
	v_div_fmas_f32 v79, v79, v200, v206
	v_div_fixup_f32 v75, v79, v75, 1.0
	v_mul_f32_e32 v75, 0xbf1b459e, v75
	v_mul_f32_e32 v75, 0x3fb8aa3b, v75
	v_exp_f32_e32 v75, v75
	v_mul_f32_e32 v79, v91, v83
	v_cvt_f16_f32_sdwa v83, -v79 dst_sel:WORD_1 dst_unused:UNUSED_PAD src0_sel:DWORD
	v_fma_mixlo_f16 v79, v82, v79, 0
	v_cvt_f16_f32_sdwa v75, v75 dst_sel:WORD_1 dst_unused:UNUSED_PAD src0_sel:DWORD
	v_fma_mixlo_f16 v82, v196, v87, 0
	v_fma_mixlo_f16 v87, v67, v195, v96
	v_cndmask_b32_e64 v67, v63, v61, s[6:7]
	v_cvt_pk_bf16_f32 v91, v67, s0
	v_mul_f32_e32 v67, v201, v80
	v_cvt_pk_bf16_f32 v80, v67, s0
	v_add_lshl_u32 v67, v94, v191, 22
	v_or3_b32 v95, v67, v95, v186
	v_or_b32_e32 v65, v66, v65
	v_or_b32_e32 v67, v75, v74
	v_or_b32_e32 v66, v73, v72
	global_store_dwordx4 v95, v[64:67], s[36:37] nt
	v_lshlrev_b32_e32 v72, 16, v77
	v_lshl_add_u32 v94, v194, 11, v178
	v_lshlrev_b32_e32 v66, 16, v79
	v_or_b32_e32 v65, v83, v90
	v_or_b32_e32 v64, v89, v212
	v_or_b32_sdwa v67, v66, v78 dst_sel:DWORD dst_unused:UNUSED_PAD src0_sel:DWORD src1_sel:WORD_0
	v_or_b32_sdwa v66, v72, v88 dst_sel:DWORD dst_unused:UNUSED_PAD src0_sel:DWORD src1_sel:WORD_0
	global_store_dwordx4 v95, v[64:67], s[36:37] offset:256 nt
	v_lshlrev_b32_e32 v72, 16, v93
	s_nop 0
	v_lshlrev_b32_e32 v64, 16, v82
	v_lshlrev_b32_e32 v66, 16, v85
	v_lshlrev_b32_e32 v67, 16, v87
	v_or_b32_sdwa v65, v64, v81 dst_sel:DWORD dst_unused:UNUSED_PAD src0_sel:DWORD src1_sel:WORD_0
	v_or_b32_sdwa v64, v66, v84 dst_sel:DWORD dst_unused:UNUSED_PAD src0_sel:DWORD src1_sel:WORD_0
	v_or_b32_sdwa v67, v67, v86 dst_sel:DWORD dst_unused:UNUSED_PAD src0_sel:DWORD src1_sel:WORD_0
	v_or_b32_sdwa v66, v72, v92 dst_sel:DWORD dst_unused:UNUSED_PAD src0_sel:DWORD src1_sel:WORD_0
	global_store_dwordx4 v95, v[64:67], s[36:37] offset:512 nt
	s_nop 1
	v_lshlrev_b32_e32 v64, 16, v71
	v_lshlrev_b32_e32 v66, 16, v69
	v_or_b32_sdwa v65, v64, v70 dst_sel:DWORD dst_unused:UNUSED_PAD src0_sel:DWORD src1_sel:WORD_0
	v_or_b32_sdwa v64, v66, v68 dst_sel:DWORD dst_unused:UNUSED_PAD src0_sel:DWORD src1_sel:WORD_0
	global_store_dwordx2 v95, v[64:65], s[36:37] offset:768 nt
	v_lshlrev_b32_e32 v64, 16, v91
	v_lshlrev_b32_e32 v66, 16, v203
	v_or_b32_sdwa v65, v64, v197 dst_sel:DWORD dst_unused:UNUSED_PAD src0_sel:DWORD src1_sel:WORD_0
	v_or_b32_sdwa v64, v66, v209 dst_sel:DWORD dst_unused:UNUSED_PAD src0_sel:DWORD src1_sel:WORD_0
	global_store_dwordx2 v94, v[64:65], s[38:39] nt
	v_lshlrev_b32_e32 v64, 16, v80
	v_lshlrev_b32_e32 v66, 16, v204
	v_or_b32_sdwa v65, v64, v198 dst_sel:DWORD dst_unused:UNUSED_PAD src0_sel:DWORD src1_sel:WORD_0
	v_or_b32_sdwa v64, v66, v210 dst_sel:DWORD dst_unused:UNUSED_PAD src0_sel:DWORD src1_sel:WORD_0
	global_store_dwordx2 v94, v[64:65], s[70:71] nt
	s_cbranch_scc0 .LBB0_383
	s_mov_b32 s6, 16
	s_mov_b64 s[0:1], 0
	s_and_b64 vcc, exec, s[82:83]
	s_cbranch_vccz .LBB0_382
	s_mov_b32 s6, 1
	s_and_b64 vcc, exec, s[80:81]
	s_cbranch_vccz .LBB0_381
	s_add_i32 s51, s51, s94
	s_add_i32 s3, s3, s42
	s_cmpk_lt_i32 s51, 0x100
	s_barrier
	s_cbranch_scc1 .LBB0_336
